# k14 + the same code touch in the GEMM2 loops (before the mid and final epilogues) and the GEMM3 loop (before the fused epilogue)
# speedup vs baseline: 1.0372x; 1.0021x over previous
.LBB0_815:
	v_lshrrev_b32_e32 v16, 1, v14
	v_and_b32_e32 v15, 15, v14
	v_and_b32_e32 v163, 24, v16
	v_lshlrev_b32_e32 v14, 2, v14
	v_lshl_or_b32 v162, s15, 6, v15
	v_lshlrev_b32_e32 v16, 1, v163
	v_lshlrev_b32_e32 v15, 6, v15
	v_and_b32_e32 v14, 32, v14
	v_or_b32_e32 v17, v15, v16
	v_lshlrev_b32_e32 v132, 7, v162
	v_bitop3_b32 v15, v15, v14, v16 bitop3:0x36
	s_movk_i32 s9, 0xe000
	v_and_or_b32 v15, v132, s9, v15
	s_lshl_b32 s9, s16, 5
	s_mov_b64 s[16:17], 0x80
	s_and_b32 s18, s9, 0x60
	s_add_i32 m0, s19, 0x18000
	v_lshl_add_u64 v[6:7], v[6:7], 0, s[16:17]
	s_lshl_b32 s9, s18, 7
	s_waitcnt vmcnt(4)
	s_barrier
	global_load_lds_dwordx4 v[6:7], off
	v_lshl_add_u64 v[4:5], v[4:5], 0, s[16:17]
	s_add_i32 m0, s19, 0x1a000
	s_add_i32 s23, s19, 0x8000
	s_add_i32 s24, s19, 0xa000
	global_load_lds_dwordx4 v[4:5], off
	v_lshl_add_u64 v[2:3], v[2:3], 0, s[16:17]
	s_mov_b32 m0, s23
	s_add_u32 s0, s0, 0x40080
	global_load_lds_dwordx4 v[2:3], off
	v_lshl_add_u64 v[0:1], v[0:1], 0, s[16:17]
	s_mov_b32 m0, s24
	s_addc_u32 s1, s1, 0
	global_load_lds_dwordx4 v[0:1], off
	s_add_i32 m0, s19, 0x1c000
	v_lshl_add_u64 v[0:1], s[0:1], 0, v[150:151]
	global_load_lds_dwordx4 v[0:1], off
	v_lshl_add_u64 v[0:1], s[0:1], 0, v[154:155]
	s_add_i32 m0, s19, 0x1e000
	s_lshl_b32 s1, s5, 5
	global_load_lds_dwordx4 v[0:1], off
	s_mul_i32 s0, s5, 33
	s_cmp_lt_i32 s5, 0
	s_cselect_b32 s5, s0, s1
	s_add_i32 s5, s5, s14
	s_ashr_i32 s0, s5, 31
	s_lshr_b32 s0, s0, 27
	s_add_i32 s0, s5, s0
	s_ashr_i32 s72, s0, 5
	v_bitop3_b32 v14, v17, s9, v14 bitop3:0xde
	s_lshl_b32 s9, s72, 3
	s_sub_i32 s1, 64, s9
	s_min_u32 s14, s1, 8
	s_andn2_b32 s0, s0, 31
	s_sub_i32 s15, s5, s0
	v_cvt_f32_ubyte0_e32 v1, s14
	v_cvt_f32_i32_e32 v0, s15
	v_rcp_iflag_f32_e32 v2, v1
	s_ashr_i32 s0, s15, 30
	s_or_b32 s26, s0, 1
	v_mov_b32_e32 v157, v151
	v_mul_f32_e32 v2, v0, v2
	v_trunc_f32_e32 v2, v2
	v_fma_f32 v0, -v2, v1, v0
	v_cvt_i32_f32_e32 v2, v2
	v_cmp_ge_f32_e64 s[0:1], |v0|, v1
	s_and_b64 s[0:1], s[0:1], exec
	s_cselect_b32 s0, s26, 0
	v_readfirstlane_b32 s1, v2
	s_add_i32 s0, s1, s0
	s_mul_i32 s73, s0, s14
	s_sub_i32 s1, s15, s73
	s_sext_i32_i8 s1, s1
	s_add_i32 s14, s9, s1
	s_ashr_i32 s15, s14, 31
	s_lshl_b64 s[58:59], s[14:15], 19
	s_add_u32 s1, s2, s58
	s_addc_u32 s2, s3, s59
	s_add_u32 s1, s1, 0x400
	s_addc_u32 s15, s2, 0
	s_bfe_i64 s[2:3], s[0:1], 0x80000
	s_lshl_b64 s[2:3], s[2:3], 19
	s_add_u32 s25, s25, s2
	s_addc_u32 s26, s33, s3
	v_lshlrev_b32_e32 v0, 14, v8
	s_add_u32 s25, s25, 0x400
	v_and_b32_e32 v0, 0xffff8000, v0
	s_addc_u32 s33, s26, 0
	v_lshl_add_u32 v0, v9, 11, v0
	v_and_b32_e32 v1, 1, v8
	s_add_u32 s36, s78, s36
	v_lshl_or_b32 v0, v1, 6, v0
	s_addc_u32 s37, s79, s37
	v_lshl_add_u32 v156, v10, 1, v0
	v_lshl_add_u64 v[0:1], s[36:37], 0, v[156:157]
	s_mov_b64 s[58:59], 0xcd88080
	v_lshl_add_u64 v[128:129], v[0:1], 0, s[58:59]
	v_lshlrev_b32_e32 v0, 14, v11
	v_and_b32_e32 v0, 0xffff8000, v0
	s_add_u32 s26, s78, s38
	v_lshl_add_u32 v0, v12, 11, v0
	v_and_b32_e32 v1, 1, v11
	s_addc_u32 s27, s79, s39
	v_lshl_or_b32 v0, v1, 6, v0
	s_add_u32 s74, s26, 0x36c8100
	s_waitcnt vmcnt(6)
	v_lshl_add_u32 v158, v13, 1, v0
	v_mov_b32_e32 v159, v151
	s_addc_u32 s75, s27, 0
	s_add_i32 s62, 0, 0x10000
	s_add_i32 s64, 0, 0x14000
	s_add_i32 s66, 0, 0x18000
	s_add_i32 s68, 0, 0x1c000
	v_lshl_add_u64 v[0:1], s[36:37], 0, v[158:159]
	v_add_u32_e32 v164, s62, v14
	v_add_u32_e32 v166, s64, v14
	s_add_i32 s62, s62, s56
	s_add_i32 s64, s64, s56
	v_add_u32_e32 v167, s66, v14
	v_add_u32_e32 v168, s68, v14
	s_add_i32 s66, s66, s56
	s_add_i32 s68, s68, s56
	v_lshl_add_u64 v[130:131], v[0:1], 0, s[58:59]
	s_mov_b32 s80, -2
	s_mov_b64 s[38:39], 0
	v_add_u32_e32 v165, 0, v15
	s_add_i32 s60, s19, 0xc000
	s_add_i32 s61, s19, 0xe000
	s_add_i32 s63, s62, 0x2000
	s_add_i32 s65, s64, 0x2000
	s_add_i32 s67, s66, 0x2000
	s_add_i32 s69, s68, 0x2000
	v_mov_b32_e32 v0, v151
	v_mov_b32_e32 v1, v151
	v_mov_b32_e32 v2, v151
	v_mov_b32_e32 v3, v151
	v_mov_b32_e32 v4, v151
	v_mov_b32_e32 v5, v151
	v_mov_b32_e32 v6, v151
	v_mov_b32_e32 v7, v151
	v_mov_b32_e32 v12, v151
	v_mov_b32_e32 v13, v151
	v_mov_b32_e32 v14, v151
	v_mov_b32_e32 v15, v151
	v_mov_b32_e32 v20, v151
	v_mov_b32_e32 v21, v151
	v_mov_b32_e32 v22, v151
	v_mov_b32_e32 v23, v151
	v_mov_b32_e32 v28, v151
	v_mov_b32_e32 v29, v151
	v_mov_b32_e32 v30, v151
	v_mov_b32_e32 v31, v151
	v_mov_b32_e32 v36, v151
	v_mov_b32_e32 v37, v151
	v_mov_b32_e32 v38, v151
	v_mov_b32_e32 v39, v151
	v_mov_b32_e32 v44, v151
	v_mov_b32_e32 v45, v151
	v_mov_b32_e32 v46, v151
	v_mov_b32_e32 v47, v151
	v_mov_b32_e32 v52, v151
	v_mov_b32_e32 v53, v151
	v_mov_b32_e32 v54, v151
	v_mov_b32_e32 v55, v151
	v_mov_b32_e32 v8, v151
	v_mov_b32_e32 v9, v151
	v_mov_b32_e32 v10, v151
	v_mov_b32_e32 v11, v151
	v_mov_b32_e32 v16, v151
	v_mov_b32_e32 v17, v151
	v_mov_b32_e32 v18, v151
	v_mov_b32_e32 v19, v151
	v_mov_b32_e32 v24, v151
	v_mov_b32_e32 v25, v151
	v_mov_b32_e32 v26, v151
	v_mov_b32_e32 v27, v151
	v_mov_b32_e32 v32, v151
	v_mov_b32_e32 v33, v151
	v_mov_b32_e32 v34, v151
	v_mov_b32_e32 v35, v151
	v_mov_b32_e32 v40, v151
	v_mov_b32_e32 v41, v151
	v_mov_b32_e32 v42, v151
	v_mov_b32_e32 v43, v151
	v_mov_b32_e32 v48, v151
	v_mov_b32_e32 v49, v151
	v_mov_b32_e32 v50, v151
	v_mov_b32_e32 v51, v151
	v_mov_b32_e32 v56, v151
	v_mov_b32_e32 v57, v151
	v_mov_b32_e32 v58, v151
	v_mov_b32_e32 v59, v151
	v_mov_b32_e32 v60, v151
	v_mov_b32_e32 v61, v151
	v_mov_b32_e32 v62, v151
	v_mov_b32_e32 v63, v151
	v_mov_b32_e32 v64, v151
	v_mov_b32_e32 v65, v151
	v_mov_b32_e32 v66, v151
	v_mov_b32_e32 v67, v151
	v_mov_b32_e32 v68, v151
	v_mov_b32_e32 v69, v151
	v_mov_b32_e32 v70, v151
	v_mov_b32_e32 v71, v151
	v_mov_b32_e32 v72, v151
	v_mov_b32_e32 v73, v151
	v_mov_b32_e32 v74, v151
	v_mov_b32_e32 v75, v151
	v_mov_b32_e32 v80, v151
	v_mov_b32_e32 v81, v151
	v_mov_b32_e32 v82, v151
	v_mov_b32_e32 v83, v151
	v_mov_b32_e32 v88, v151
	v_mov_b32_e32 v89, v151
	v_mov_b32_e32 v90, v151
	v_mov_b32_e32 v91, v151
	v_mov_b32_e32 v96, v151
	v_mov_b32_e32 v97, v151
	v_mov_b32_e32 v98, v151
	v_mov_b32_e32 v99, v151
	v_mov_b32_e32 v104, v151
	v_mov_b32_e32 v105, v151
	v_mov_b32_e32 v106, v151
	v_mov_b32_e32 v107, v151
	v_mov_b32_e32 v108, v151
	v_mov_b32_e32 v109, v151
	v_mov_b32_e32 v110, v151
	v_mov_b32_e32 v111, v151
	v_mov_b32_e32 v76, v151
	v_mov_b32_e32 v77, v151
	v_mov_b32_e32 v78, v151
	v_mov_b32_e32 v79, v151
	v_mov_b32_e32 v84, v151
	v_mov_b32_e32 v85, v151
	v_mov_b32_e32 v86, v151
	v_mov_b32_e32 v87, v151
	v_mov_b32_e32 v92, v151
	v_mov_b32_e32 v93, v151
	v_mov_b32_e32 v94, v151
	v_mov_b32_e32 v95, v151
	v_mov_b32_e32 v100, v151
	v_mov_b32_e32 v101, v151
	v_mov_b32_e32 v102, v151
	v_mov_b32_e32 v103, v151
	v_mov_b32_e32 v112, v151
	v_mov_b32_e32 v113, v151
	v_mov_b32_e32 v114, v151
	v_mov_b32_e32 v115, v151
	v_mov_b32_e32 v116, v151
	v_mov_b32_e32 v117, v151
	v_mov_b32_e32 v118, v151
	v_mov_b32_e32 v119, v151
	v_mov_b32_e32 v120, v151
	v_mov_b32_e32 v121, v151
	v_mov_b32_e32 v122, v151
	v_mov_b32_e32 v123, v151
	v_mov_b32_e32 v124, v151
	v_mov_b32_e32 v125, v151
	v_mov_b32_e32 v126, v151
	v_mov_b32_e32 v127, v151
	s_barrier
	s_getpc_b64 s[98:99]
	v_lshlrev_b32_e32 v246, 7, v202
	v_mov_b32_e32 v247, 0
	v_lshl_add_u64 v[246:247], v[246:247], 0, s[98:99]
.LBB0_816:
	s_add_u32 s26, s36, s38
	ds_read_b128 v[134:137], v164
	ds_read_b128 v[138:141], v164 offset:1024
	ds_read_b128 v[142:145], v164 offset:2048
	ds_read_b128 v[170:173], v164 offset:3072
	s_addc_u32 s27, s37, s39
	s_add_u32 s26, s26, 0xcd48100
	s_addc_u32 s27, s27, 0
	s_add_u32 s56, s74, s38
	s_addc_u32 s57, s75, s39
	s_cmpk_eq_i32 s38, 0x300
	s_cselect_b32 s59, s15, s27
	s_cselect_b32 s58, s1, s26
	s_cselect_b32 s57, s33, s57
	s_cselect_b32 s56, s25, s56
	s_mov_b32 m0, s60
	v_lshl_add_u64 v[146:147], v[128:129], 0, s[38:39]
	ds_read_b128 v[174:177], v165
	ds_read_b128 v[178:181], v165 offset:1024
	ds_read_b128 v[182:185], v165 offset:2048
	ds_read_b128 v[186:189], v165 offset:3072
	ds_read_b128 v[190:193], v165 offset:4096
	ds_read_b128 v[194:197], v165 offset:5120
	ds_read_b128 v[198:201], v165 offset:6144
	ds_read_b128 v[210:213], v165 offset:7168
	global_load_lds_dwordx4 v[146:147], off
	v_lshl_add_u64 v[146:147], v[130:131], 0, s[38:39]
	s_mov_b32 m0, s61
	s_nop 0
	global_load_lds_dwordx4 v[146:147], off
	s_cmpk_eq_i32 s38, 0x100
	s_cbranch_scc0 .Lct_g2a
	global_load_dword v248, v[246:247], off
.Lct_g2a:
	s_waitcnt lgkmcnt(8)
	s_barrier
	s_waitcnt lgkmcnt(0)
	s_setprio 1
	s_waitcnt lgkmcnt(0)
	v_mfma_f32_16x16x32_bf16 v[124:127], v[134:137], v[174:177], v[124:127]
	v_mfma_f32_16x16x32_bf16 v[120:123], v[142:145], v[174:177], v[120:123]
	v_mfma_f32_16x16x32_bf16 v[116:119], v[134:137], v[182:185], v[116:119]
	v_mfma_f32_16x16x32_bf16 v[112:115], v[142:145], v[182:185], v[112:115]
	v_mfma_f32_16x16x32_bf16 v[100:103], v[134:137], v[190:193], v[100:103]
	v_mfma_f32_16x16x32_bf16 v[92:95], v[142:145], v[190:193], v[92:95]
	v_mfma_f32_16x16x32_bf16 v[84:87], v[134:137], v[198:201], v[84:87]
	v_mfma_f32_16x16x32_bf16 v[76:79], v[142:145], v[198:201], v[76:79]
	v_mfma_f32_16x16x32_bf16 v[124:127], v[138:141], v[178:181], v[124:127]
	v_mfma_f32_16x16x32_bf16 v[120:123], v[170:173], v[178:181], v[120:123]
	v_mfma_f32_16x16x32_bf16 v[116:119], v[138:141], v[186:189], v[116:119]
	v_mfma_f32_16x16x32_bf16 v[112:115], v[170:173], v[186:189], v[112:115]
	v_mfma_f32_16x16x32_bf16 v[100:103], v[138:141], v[194:197], v[100:103]
	v_mfma_f32_16x16x32_bf16 v[92:95], v[170:173], v[194:197], v[92:95]
	v_mfma_f32_16x16x32_bf16 v[84:87], v[138:141], v[210:213], v[84:87]
	v_mfma_f32_16x16x32_bf16 v[76:79], v[170:173], v[210:213], v[76:79]
	s_setprio 0
	s_barrier
	s_mov_b32 m0, s62
	v_lshl_add_u64 v[146:147], s[56:57], 0, v[150:151]
	ds_read_b128 v[214:217], v166
	ds_read_b128 v[218:221], v166 offset:1024
	ds_read_b128 v[222:225], v166 offset:2048
	ds_read_b128 v[226:229], v166 offset:3072
	global_load_lds_dwordx4 v[146:147], off
	v_lshl_add_u64 v[160:161], s[56:57], 0, v[154:155]
	s_mov_b32 m0, s63
	s_nop 0
	global_load_lds_dwordx4 v[160:161], off
	s_barrier
	s_waitcnt lgkmcnt(0)
	s_setprio 1
	s_waitcnt lgkmcnt(0)
	v_mfma_f32_16x16x32_bf16 v[108:111], v[214:217], v[174:177], v[108:111]
	v_mfma_f32_16x16x32_bf16 v[104:107], v[222:225], v[174:177], v[104:107]
	v_mfma_f32_16x16x32_bf16 v[96:99], v[214:217], v[182:185], v[96:99]
	v_mfma_f32_16x16x32_bf16 v[88:91], v[222:225], v[182:185], v[88:91]
	v_mfma_f32_16x16x32_bf16 v[80:83], v[214:217], v[190:193], v[80:83]
	v_mfma_f32_16x16x32_bf16 v[72:75], v[222:225], v[190:193], v[72:75]
	v_mfma_f32_16x16x32_bf16 v[68:71], v[214:217], v[198:201], v[68:71]
	v_mfma_f32_16x16x32_bf16 v[64:67], v[222:225], v[198:201], v[64:67]
	v_mfma_f32_16x16x32_bf16 v[108:111], v[218:221], v[178:181], v[108:111]
	v_mfma_f32_16x16x32_bf16 v[104:107], v[226:229], v[178:181], v[104:107]
	v_mfma_f32_16x16x32_bf16 v[96:99], v[218:221], v[186:189], v[96:99]
	v_mfma_f32_16x16x32_bf16 v[88:91], v[226:229], v[186:189], v[88:91]
	v_mfma_f32_16x16x32_bf16 v[80:83], v[218:221], v[194:197], v[80:83]
	v_mfma_f32_16x16x32_bf16 v[72:75], v[226:229], v[194:197], v[72:75]
	v_mfma_f32_16x16x32_bf16 v[68:71], v[218:221], v[210:213], v[68:71]
	v_mfma_f32_16x16x32_bf16 v[64:67], v[226:229], v[210:213], v[64:67]
	s_setprio 0
	s_mov_b32 m0, s19
	v_lshl_add_u64 v[230:231], s[58:59], 0, v[148:149]
	s_barrier
	ds_read_b128 v[174:177], v165 offset:16384
	ds_read_b128 v[178:181], v165 offset:17408
	ds_read_b128 v[182:185], v165 offset:18432
	ds_read_b128 v[186:189], v165 offset:19456
	ds_read_b128 v[190:193], v165 offset:20480
	ds_read_b128 v[194:197], v165 offset:21504
	ds_read_b128 v[198:201], v165 offset:22528
	ds_read_b128 v[210:213], v165 offset:23552
	global_load_lds_dwordx4 v[230:231], off
	v_lshl_add_u64 v[232:233], s[58:59], 0, v[152:153]
	s_mov_b32 m0, s20
	s_nop 0
	global_load_lds_dwordx4 v[232:233], off
	s_barrier
	s_waitcnt lgkmcnt(0)
	s_setprio 1
	s_waitcnt lgkmcnt(0)
	v_mfma_f32_16x16x32_bf16 v[60:63], v[134:137], v[174:177], v[60:63]
	v_mfma_f32_16x16x32_bf16 v[56:59], v[142:145], v[174:177], v[56:59]
	v_mfma_f32_16x16x32_bf16 v[48:51], v[134:137], v[182:185], v[48:51]
	v_mfma_f32_16x16x32_bf16 v[40:43], v[142:145], v[182:185], v[40:43]
	v_mfma_f32_16x16x32_bf16 v[32:35], v[134:137], v[190:193], v[32:35]
	v_mfma_f32_16x16x32_bf16 v[24:27], v[142:145], v[190:193], v[24:27]
	v_mfma_f32_16x16x32_bf16 v[16:19], v[134:137], v[198:201], v[16:19]
	v_mfma_f32_16x16x32_bf16 v[8:11], v[142:145], v[198:201], v[8:11]
	v_mfma_f32_16x16x32_bf16 v[60:63], v[138:141], v[178:181], v[60:63]
	v_mfma_f32_16x16x32_bf16 v[56:59], v[170:173], v[178:181], v[56:59]
	v_mfma_f32_16x16x32_bf16 v[48:51], v[138:141], v[186:189], v[48:51]
	v_mfma_f32_16x16x32_bf16 v[40:43], v[170:173], v[186:189], v[40:43]
	v_mfma_f32_16x16x32_bf16 v[32:35], v[138:141], v[194:197], v[32:35]
	v_mfma_f32_16x16x32_bf16 v[24:27], v[170:173], v[194:197], v[24:27]
	v_mfma_f32_16x16x32_bf16 v[16:19], v[138:141], v[210:213], v[16:19]
	v_mfma_f32_16x16x32_bf16 v[8:11], v[170:173], v[210:213], v[8:11]
	s_setprio 0
	s_barrier
	s_add_u32 s82, s56, 0x40000
	s_addc_u32 s83, s57, 0
	s_mov_b32 m0, s64
	v_lshl_add_u64 v[134:135], s[82:83], 0, v[150:151]
	global_load_lds_dwordx4 v[134:135], off
	v_lshl_add_u64 v[134:135], s[82:83], 0, v[154:155]
	s_mov_b32 m0, s65
	s_nop 0
	global_load_lds_dwordx4 v[134:135], off
	s_waitcnt vmcnt(6)
	s_barrier
	s_setprio 1
	v_mfma_f32_16x16x32_bf16 v[52:55], v[214:217], v[174:177], v[52:55]
	v_mfma_f32_16x16x32_bf16 v[44:47], v[222:225], v[174:177], v[44:47]
	v_mfma_f32_16x16x32_bf16 v[36:39], v[214:217], v[182:185], v[36:39]
	v_mfma_f32_16x16x32_bf16 v[28:31], v[222:225], v[182:185], v[28:31]
	v_mfma_f32_16x16x32_bf16 v[20:23], v[214:217], v[190:193], v[20:23]
	v_mfma_f32_16x16x32_bf16 v[12:15], v[222:225], v[190:193], v[12:15]
	v_mfma_f32_16x16x32_bf16 v[4:7], v[214:217], v[198:201], v[4:7]
	v_mfma_f32_16x16x32_bf16 v[0:3], v[222:225], v[198:201], v[0:3]
	v_mfma_f32_16x16x32_bf16 v[52:55], v[218:221], v[178:181], v[52:55]
	v_mfma_f32_16x16x32_bf16 v[44:47], v[226:229], v[178:181], v[44:47]
	v_mfma_f32_16x16x32_bf16 v[36:39], v[218:221], v[186:189], v[36:39]
	v_mfma_f32_16x16x32_bf16 v[28:31], v[226:229], v[186:189], v[28:31]
	v_mfma_f32_16x16x32_bf16 v[20:23], v[218:221], v[194:197], v[20:23]
	v_mfma_f32_16x16x32_bf16 v[12:15], v[226:229], v[194:197], v[12:15]
	v_mfma_f32_16x16x32_bf16 v[4:7], v[218:221], v[210:213], v[4:7]
	v_mfma_f32_16x16x32_bf16 v[0:3], v[226:229], v[210:213], v[0:3]
	s_setprio 0
	s_barrier
	ds_read_b128 v[134:137], v167
	ds_read_b128 v[138:141], v167 offset:1024
	ds_read_b128 v[142:145], v167 offset:2048
	ds_read_b128 v[170:173], v167 offset:3072
	s_add_u32 s58, s58, 0x40000
	s_addc_u32 s59, s59, 0
	s_mov_b32 m0, s21
	v_lshl_add_u64 v[214:215], s[58:59], 0, v[148:149]
	ds_read_b128 v[174:177], v165 offset:32768
	ds_read_b128 v[178:181], v165 offset:33792
	ds_read_b128 v[182:185], v165 offset:34816
	ds_read_b128 v[186:189], v165 offset:35840
	ds_read_b128 v[190:193], v165 offset:36864
	ds_read_b128 v[194:197], v165 offset:37888
	ds_read_b128 v[198:201], v165 offset:38912
	ds_read_b128 v[210:213], v165 offset:39936
	global_load_lds_dwordx4 v[214:215], off
	v_lshl_add_u64 v[214:215], s[58:59], 0, v[152:153]
	s_mov_b32 m0, s22
	s_nop 0
	global_load_lds_dwordx4 v[214:215], off
	s_waitcnt lgkmcnt(8)
	s_barrier
	s_waitcnt lgkmcnt(0)
	s_setprio 1
	s_waitcnt lgkmcnt(0)
	v_mfma_f32_16x16x32_bf16 v[124:127], v[134:137], v[174:177], v[124:127]
	v_mfma_f32_16x16x32_bf16 v[120:123], v[142:145], v[174:177], v[120:123]
	v_mfma_f32_16x16x32_bf16 v[116:119], v[134:137], v[182:185], v[116:119]
	v_mfma_f32_16x16x32_bf16 v[112:115], v[142:145], v[182:185], v[112:115]
	v_mfma_f32_16x16x32_bf16 v[100:103], v[134:137], v[190:193], v[100:103]
	v_mfma_f32_16x16x32_bf16 v[92:95], v[142:145], v[190:193], v[92:95]
	v_mfma_f32_16x16x32_bf16 v[84:87], v[134:137], v[198:201], v[84:87]
	v_mfma_f32_16x16x32_bf16 v[76:79], v[142:145], v[198:201], v[76:79]
	v_mfma_f32_16x16x32_bf16 v[124:127], v[138:141], v[178:181], v[124:127]
	v_mfma_f32_16x16x32_bf16 v[120:123], v[170:173], v[178:181], v[120:123]
	v_mfma_f32_16x16x32_bf16 v[116:119], v[138:141], v[186:189], v[116:119]
	v_mfma_f32_16x16x32_bf16 v[112:115], v[170:173], v[186:189], v[112:115]
	v_mfma_f32_16x16x32_bf16 v[100:103], v[138:141], v[194:197], v[100:103]
	v_mfma_f32_16x16x32_bf16 v[92:95], v[170:173], v[194:197], v[92:95]
	v_mfma_f32_16x16x32_bf16 v[84:87], v[138:141], v[210:213], v[84:87]
	v_mfma_f32_16x16x32_bf16 v[76:79], v[170:173], v[210:213], v[76:79]
	s_setprio 0
	s_barrier
	s_mov_b32 m0, s66
	v_lshl_add_u64 v[146:147], v[146:147], 0, s[16:17]
	ds_read_b128 v[214:217], v168
	ds_read_b128 v[218:221], v168 offset:1024
	ds_read_b128 v[222:225], v168 offset:2048
	ds_read_b128 v[226:229], v168 offset:3072
	global_load_lds_dwordx4 v[146:147], off
	v_lshl_add_u64 v[146:147], v[160:161], 0, s[16:17]
	s_mov_b32 m0, s67
	s_nop 0
	global_load_lds_dwordx4 v[146:147], off
	s_barrier
	s_waitcnt lgkmcnt(0)
	s_setprio 1
	s_waitcnt lgkmcnt(0)
	v_mfma_f32_16x16x32_bf16 v[108:111], v[214:217], v[174:177], v[108:111]
	v_mfma_f32_16x16x32_bf16 v[104:107], v[222:225], v[174:177], v[104:107]
	v_mfma_f32_16x16x32_bf16 v[96:99], v[214:217], v[182:185], v[96:99]
	v_mfma_f32_16x16x32_bf16 v[88:91], v[222:225], v[182:185], v[88:91]
	v_mfma_f32_16x16x32_bf16 v[80:83], v[214:217], v[190:193], v[80:83]
	v_mfma_f32_16x16x32_bf16 v[72:75], v[222:225], v[190:193], v[72:75]
	v_mfma_f32_16x16x32_bf16 v[68:71], v[214:217], v[198:201], v[68:71]
	v_mfma_f32_16x16x32_bf16 v[64:67], v[222:225], v[198:201], v[64:67]
	v_mfma_f32_16x16x32_bf16 v[108:111], v[218:221], v[178:181], v[108:111]
	v_mfma_f32_16x16x32_bf16 v[104:107], v[226:229], v[178:181], v[104:107]
	v_mfma_f32_16x16x32_bf16 v[96:99], v[218:221], v[186:189], v[96:99]
	v_mfma_f32_16x16x32_bf16 v[88:91], v[226:229], v[186:189], v[88:91]
	v_mfma_f32_16x16x32_bf16 v[80:83], v[218:221], v[194:197], v[80:83]
	v_mfma_f32_16x16x32_bf16 v[72:75], v[226:229], v[194:197], v[72:75]
	v_mfma_f32_16x16x32_bf16 v[68:71], v[218:221], v[210:213], v[68:71]
	v_mfma_f32_16x16x32_bf16 v[64:67], v[226:229], v[210:213], v[64:67]
	s_setprio 0
	s_mov_b32 m0, s23
	v_lshl_add_u64 v[146:147], v[230:231], 0, s[16:17]
	s_barrier
	ds_read_b128 v[174:177], v165 offset:49152
	ds_read_b128 v[178:181], v165 offset:50176
	ds_read_b128 v[182:185], v165 offset:51200
	ds_read_b128 v[186:189], v165 offset:52224
	ds_read_b128 v[190:193], v165 offset:53248
	ds_read_b128 v[194:197], v165 offset:54272
	ds_read_b128 v[198:201], v165 offset:55296
	ds_read_b128 v[210:213], v165 offset:56320
	global_load_lds_dwordx4 v[146:147], off
	v_lshl_add_u64 v[146:147], v[232:233], 0, s[16:17]
	s_mov_b32 m0, s24
	s_nop 0
	global_load_lds_dwordx4 v[146:147], off
	s_barrier
	s_waitcnt lgkmcnt(0)
	s_setprio 1
	s_waitcnt lgkmcnt(0)
	v_mfma_f32_16x16x32_bf16 v[60:63], v[134:137], v[174:177], v[60:63]
	v_mfma_f32_16x16x32_bf16 v[56:59], v[142:145], v[174:177], v[56:59]
	v_mfma_f32_16x16x32_bf16 v[48:51], v[134:137], v[182:185], v[48:51]
	v_mfma_f32_16x16x32_bf16 v[40:43], v[142:145], v[182:185], v[40:43]
	v_mfma_f32_16x16x32_bf16 v[32:35], v[134:137], v[190:193], v[32:35]
	v_mfma_f32_16x16x32_bf16 v[24:27], v[142:145], v[190:193], v[24:27]
	v_mfma_f32_16x16x32_bf16 v[16:19], v[134:137], v[198:201], v[16:19]
	v_mfma_f32_16x16x32_bf16 v[8:11], v[142:145], v[198:201], v[8:11]
	v_mfma_f32_16x16x32_bf16 v[60:63], v[138:141], v[178:181], v[60:63]
	v_mfma_f32_16x16x32_bf16 v[56:59], v[170:173], v[178:181], v[56:59]
	v_mfma_f32_16x16x32_bf16 v[48:51], v[138:141], v[186:189], v[48:51]
	v_mfma_f32_16x16x32_bf16 v[40:43], v[170:173], v[186:189], v[40:43]
	v_mfma_f32_16x16x32_bf16 v[32:35], v[138:141], v[194:197], v[32:35]
	v_mfma_f32_16x16x32_bf16 v[24:27], v[170:173], v[194:197], v[24:27]
	v_mfma_f32_16x16x32_bf16 v[16:19], v[138:141], v[210:213], v[16:19]
	v_mfma_f32_16x16x32_bf16 v[8:11], v[170:173], v[210:213], v[8:11]
	s_setprio 0
	s_barrier
	s_add_u32 s56, s56, 0x40080
	s_addc_u32 s57, s57, 0
	s_mov_b32 m0, s68
	v_lshl_add_u64 v[134:135], s[56:57], 0, v[150:151]
	global_load_lds_dwordx4 v[134:135], off
	v_lshl_add_u64 v[134:135], s[56:57], 0, v[154:155]
	s_mov_b32 m0, s69
	s_nop 0
	global_load_lds_dwordx4 v[134:135], off
	s_waitcnt vmcnt(6)
	s_barrier
	s_setprio 1
	v_mfma_f32_16x16x32_bf16 v[52:55], v[214:217], v[174:177], v[52:55]
	v_mfma_f32_16x16x32_bf16 v[44:47], v[222:225], v[174:177], v[44:47]
	v_mfma_f32_16x16x32_bf16 v[36:39], v[214:217], v[182:185], v[36:39]
	v_mfma_f32_16x16x32_bf16 v[28:31], v[222:225], v[182:185], v[28:31]
	v_mfma_f32_16x16x32_bf16 v[20:23], v[214:217], v[190:193], v[20:23]
	v_mfma_f32_16x16x32_bf16 v[12:15], v[222:225], v[190:193], v[12:15]
	v_mfma_f32_16x16x32_bf16 v[4:7], v[214:217], v[198:201], v[4:7]
	v_mfma_f32_16x16x32_bf16 v[0:3], v[222:225], v[198:201], v[0:3]
	v_mfma_f32_16x16x32_bf16 v[52:55], v[218:221], v[178:181], v[52:55]
	v_mfma_f32_16x16x32_bf16 v[44:47], v[226:229], v[178:181], v[44:47]
	v_mfma_f32_16x16x32_bf16 v[36:39], v[218:221], v[186:189], v[36:39]
	v_mfma_f32_16x16x32_bf16 v[28:31], v[226:229], v[186:189], v[28:31]
	v_mfma_f32_16x16x32_bf16 v[20:23], v[218:221], v[194:197], v[20:23]
	v_mfma_f32_16x16x32_bf16 v[12:15], v[226:229], v[194:197], v[12:15]
	v_mfma_f32_16x16x32_bf16 v[4:7], v[218:221], v[210:213], v[4:7]
	v_mfma_f32_16x16x32_bf16 v[0:3], v[226:229], v[210:213], v[0:3]
	s_setprio 0
	s_add_i32 s80, s80, 2
	s_add_u32 s38, s38, 0x100
	s_addc_u32 s39, s39, 0
	s_cmp_gt_u32 s80, 5
	s_barrier
	s_cbranch_scc0 .LBB0_816
	s_cmpk_gt_u32 s13, 0xff
	s_cbranch_scc1 .Lus3
	s_barrier

.Lus4:
	s_getpc_b64 s[98:99]
	v_lshlrev_b32_e32 v246, 7, v202
	v_mov_b32_e32 v247, 0
	v_lshl_add_u64 v[246:247], v[246:247], 0, s[98:99]
.LBB0_818:
	s_add_u32 s16, s2, s4
	ds_read_b128 v[84:87], v164
	ds_read_b128 v[136:139], v164 offset:1024
	ds_read_b128 v[140:143], v164 offset:2048
	ds_read_b128 v[144:147], v164 offset:3072
	s_addc_u32 s17, s3, s5
	s_add_u32 s16, s16, 0xcd48500
	s_addc_u32 s17, s17, 0
	s_add_u32 s26, s38, s4
	s_addc_u32 s27, s39, s5
	s_cmpk_eq_i32 s4, 0x300
	s_cselect_b32 s37, s15, s17
	s_cselect_b32 s36, s1, s16
	s_cselect_b32 s17, s33, s27
	s_cselect_b32 s16, s25, s26
	s_mov_b32 m0, s60
	v_lshl_add_u64 v[160:161], v[16:17], 0, s[4:5]
	ds_read_b128 v[156:159], v165
	ds_read_b128 v[170:173], v165 offset:1024
	ds_read_b128 v[174:177], v165 offset:2048
	ds_read_b128 v[178:181], v165 offset:3072
	ds_read_b128 v[182:185], v165 offset:4096
	ds_read_b128 v[186:189], v165 offset:5120
	ds_read_b128 v[190:193], v165 offset:6144
	ds_read_b128 v[194:197], v165 offset:7168
	global_load_lds_dwordx4 v[160:161], off
	v_lshl_add_u64 v[160:161], v[18:19], 0, s[4:5]
	s_mov_b32 m0, s61
	s_nop 0
	global_load_lds_dwordx4 v[160:161], off
	s_cmpk_eq_i32 s4, 0x200
	s_cbranch_scc0 .Lct_g2b
	global_load_dword v248, v[246:247], off
.Lct_g2b:
	s_waitcnt lgkmcnt(8)
	s_barrier
	s_waitcnt lgkmcnt(0)
	s_setprio 1
	s_waitcnt lgkmcnt(0)
	v_mfma_f32_16x16x32_bf16 v[124:127], v[84:87], v[156:159], v[124:127]
	v_mfma_f32_16x16x32_bf16 v[120:123], v[140:143], v[156:159], v[120:123]
	v_mfma_f32_16x16x32_bf16 v[116:119], v[84:87], v[174:177], v[116:119]
	v_mfma_f32_16x16x32_bf16 v[112:115], v[140:143], v[174:177], v[112:115]
	v_mfma_f32_16x16x32_bf16 v[96:99], v[84:87], v[182:185], v[96:99]
	v_mfma_f32_16x16x32_bf16 v[100:103], v[140:143], v[182:185], v[100:103]
	v_mfma_f32_16x16x32_bf16 v[80:83], v[84:87], v[190:193], v[80:83]
	v_mfma_f32_16x16x32_bf16 v[76:79], v[140:143], v[190:193], v[76:79]
	v_mfma_f32_16x16x32_bf16 v[124:127], v[136:139], v[170:173], v[124:127]
	v_mfma_f32_16x16x32_bf16 v[120:123], v[144:147], v[170:173], v[120:123]
	v_mfma_f32_16x16x32_bf16 v[116:119], v[136:139], v[178:181], v[116:119]
	v_mfma_f32_16x16x32_bf16 v[112:115], v[144:147], v[178:181], v[112:115]
	v_mfma_f32_16x16x32_bf16 v[96:99], v[136:139], v[186:189], v[96:99]
	v_mfma_f32_16x16x32_bf16 v[100:103], v[144:147], v[186:189], v[100:103]
	v_mfma_f32_16x16x32_bf16 v[80:83], v[136:139], v[194:197], v[80:83]
	v_mfma_f32_16x16x32_bf16 v[76:79], v[144:147], v[194:197], v[76:79]
	s_setprio 0
	s_barrier
	s_mov_b32 m0, s62
	v_lshl_add_u64 v[160:161], s[16:17], 0, v[150:151]
	ds_read_b128 v[198:201], v166
	ds_read_b128 v[210:213], v166 offset:1024
	ds_read_b128 v[214:217], v166 offset:2048
	ds_read_b128 v[218:221], v166 offset:3072
	global_load_lds_dwordx4 v[160:161], off
	v_lshl_add_u64 v[222:223], s[16:17], 0, v[154:155]
	s_mov_b32 m0, s63
	s_nop 0
	global_load_lds_dwordx4 v[222:223], off
	s_barrier
	s_waitcnt lgkmcnt(0)
	s_setprio 1
	s_waitcnt lgkmcnt(0)
	v_mfma_f32_16x16x32_bf16 v[128:131], v[198:201], v[156:159], v[128:131]
	v_mfma_f32_16x16x32_bf16 v[132:135], v[214:217], v[156:159], v[132:135]
	v_mfma_f32_16x16x32_bf16 v[104:107], v[198:201], v[174:177], v[104:107]
	v_mfma_f32_16x16x32_bf16 v[108:111], v[214:217], v[174:177], v[108:111]
	v_mfma_f32_16x16x32_bf16 v[88:91], v[198:201], v[182:185], v[88:91]
	v_mfma_f32_16x16x32_bf16 v[92:95], v[214:217], v[182:185], v[92:95]
	v_mfma_f32_16x16x32_bf16 v[68:71], v[198:201], v[190:193], v[68:71]
	v_mfma_f32_16x16x32_bf16 v[72:75], v[214:217], v[190:193], v[72:75]
	v_mfma_f32_16x16x32_bf16 v[128:131], v[210:213], v[170:173], v[128:131]
	v_mfma_f32_16x16x32_bf16 v[132:135], v[218:221], v[170:173], v[132:135]
	v_mfma_f32_16x16x32_bf16 v[104:107], v[210:213], v[178:181], v[104:107]
	v_mfma_f32_16x16x32_bf16 v[108:111], v[218:221], v[178:181], v[108:111]
	v_mfma_f32_16x16x32_bf16 v[88:91], v[210:213], v[186:189], v[88:91]
	v_mfma_f32_16x16x32_bf16 v[92:95], v[218:221], v[186:189], v[92:95]
	v_mfma_f32_16x16x32_bf16 v[68:71], v[210:213], v[194:197], v[68:71]
	v_mfma_f32_16x16x32_bf16 v[72:75], v[218:221], v[194:197], v[72:75]
	s_setprio 0
	s_mov_b32 m0, s19
	v_lshl_add_u64 v[224:225], s[36:37], 0, v[148:149]
	s_barrier
	ds_read_b128 v[156:159], v165 offset:16384
	ds_read_b128 v[170:173], v165 offset:17408
	ds_read_b128 v[174:177], v165 offset:18432
	ds_read_b128 v[178:181], v165 offset:19456
	ds_read_b128 v[182:185], v165 offset:20480
	ds_read_b128 v[186:189], v165 offset:21504
	ds_read_b128 v[190:193], v165 offset:22528
	ds_read_b128 v[194:197], v165 offset:23552
	global_load_lds_dwordx4 v[224:225], off
	v_lshl_add_u64 v[226:227], s[36:37], 0, v[152:153]
	s_mov_b32 m0, s20
	s_nop 0
	global_load_lds_dwordx4 v[226:227], off
	s_barrier
	s_waitcnt lgkmcnt(0)
	s_setprio 1
	s_waitcnt lgkmcnt(0)
	v_mfma_f32_16x16x32_bf16 v[60:63], v[84:87], v[156:159], v[60:63]
	v_mfma_f32_16x16x32_bf16 v[64:67], v[140:143], v[156:159], v[64:67]
	v_mfma_f32_16x16x32_bf16 v[44:47], v[84:87], v[174:177], v[44:47]
	v_mfma_f32_16x16x32_bf16 v[48:51], v[140:143], v[174:177], v[48:51]
	v_mfma_f32_16x16x32_bf16 v[28:31], v[84:87], v[182:185], v[28:31]
	v_mfma_f32_16x16x32_bf16 v[32:35], v[140:143], v[182:185], v[32:35]
	v_mfma_f32_16x16x32_bf16 v[12:15], v[84:87], v[190:193], v[12:15]
	v_mfma_f32_16x16x32_bf16 v[8:11], v[140:143], v[190:193], v[8:11]
	v_mfma_f32_16x16x32_bf16 v[60:63], v[136:139], v[170:173], v[60:63]
	v_mfma_f32_16x16x32_bf16 v[64:67], v[144:147], v[170:173], v[64:67]
	v_mfma_f32_16x16x32_bf16 v[44:47], v[136:139], v[178:181], v[44:47]
	v_mfma_f32_16x16x32_bf16 v[48:51], v[144:147], v[178:181], v[48:51]
	v_mfma_f32_16x16x32_bf16 v[28:31], v[136:139], v[186:189], v[28:31]
	v_mfma_f32_16x16x32_bf16 v[32:35], v[144:147], v[186:189], v[32:35]
	v_mfma_f32_16x16x32_bf16 v[12:15], v[136:139], v[194:197], v[12:15]
	v_mfma_f32_16x16x32_bf16 v[8:11], v[144:147], v[194:197], v[8:11]
	s_setprio 0
	s_barrier
	s_add_u32 s58, s16, 0x40000
	s_addc_u32 s59, s17, 0
	s_mov_b32 m0, s64
	v_lshl_add_u64 v[84:85], s[58:59], 0, v[150:151]
	global_load_lds_dwordx4 v[84:85], off
	v_lshl_add_u64 v[84:85], s[58:59], 0, v[154:155]
	s_mov_b32 m0, s65
	s_nop 0
	global_load_lds_dwordx4 v[84:85], off
	s_waitcnt vmcnt(6)
	s_barrier
	s_setprio 1
	v_mfma_f32_16x16x32_bf16 v[52:55], v[198:201], v[156:159], v[52:55]
	v_mfma_f32_16x16x32_bf16 v[56:59], v[214:217], v[156:159], v[56:59]
	v_mfma_f32_16x16x32_bf16 v[36:39], v[198:201], v[174:177], v[36:39]
	v_mfma_f32_16x16x32_bf16 v[40:43], v[214:217], v[174:177], v[40:43]
	v_mfma_f32_16x16x32_bf16 v[20:23], v[198:201], v[182:185], v[20:23]
	v_mfma_f32_16x16x32_bf16 v[24:27], v[214:217], v[182:185], v[24:27]
	v_mfma_f32_16x16x32_bf16 v[4:7], v[198:201], v[190:193], v[4:7]
	v_mfma_f32_16x16x32_bf16 v[0:3], v[214:217], v[190:193], v[0:3]
	v_mfma_f32_16x16x32_bf16 v[52:55], v[210:213], v[170:173], v[52:55]
	v_mfma_f32_16x16x32_bf16 v[56:59], v[218:221], v[170:173], v[56:59]
	v_mfma_f32_16x16x32_bf16 v[36:39], v[210:213], v[178:181], v[36:39]
	v_mfma_f32_16x16x32_bf16 v[40:43], v[218:221], v[178:181], v[40:43]
	v_mfma_f32_16x16x32_bf16 v[20:23], v[210:213], v[186:189], v[20:23]
	v_mfma_f32_16x16x32_bf16 v[24:27], v[218:221], v[186:189], v[24:27]
	v_mfma_f32_16x16x32_bf16 v[4:7], v[210:213], v[194:197], v[4:7]
	v_mfma_f32_16x16x32_bf16 v[0:3], v[218:221], v[194:197], v[0:3]
	s_setprio 0
	s_barrier
	ds_read_b128 v[84:87], v167
	ds_read_b128 v[136:139], v167 offset:1024
	ds_read_b128 v[140:143], v167 offset:2048
	ds_read_b128 v[144:147], v167 offset:3072
	s_add_u32 s36, s36, 0x40000
	s_addc_u32 s37, s37, 0
	s_mov_b32 m0, s21
	v_lshl_add_u64 v[198:199], s[36:37], 0, v[148:149]
	ds_read_b128 v[156:159], v165 offset:32768
	ds_read_b128 v[170:173], v165 offset:33792
	ds_read_b128 v[174:177], v165 offset:34816
	ds_read_b128 v[178:181], v165 offset:35840
	ds_read_b128 v[182:185], v165 offset:36864
	ds_read_b128 v[186:189], v165 offset:37888
	ds_read_b128 v[190:193], v165 offset:38912
	ds_read_b128 v[194:197], v165 offset:39936
	global_load_lds_dwordx4 v[198:199], off
	v_lshl_add_u64 v[198:199], s[36:37], 0, v[152:153]
	s_mov_b32 m0, s22
	s_nop 0
	global_load_lds_dwordx4 v[198:199], off
	s_waitcnt lgkmcnt(8)
	s_barrier
	s_waitcnt lgkmcnt(0)
	s_setprio 1
	s_waitcnt lgkmcnt(0)
	v_mfma_f32_16x16x32_bf16 v[124:127], v[84:87], v[156:159], v[124:127]
	v_mfma_f32_16x16x32_bf16 v[120:123], v[140:143], v[156:159], v[120:123]
	v_mfma_f32_16x16x32_bf16 v[116:119], v[84:87], v[174:177], v[116:119]
	v_mfma_f32_16x16x32_bf16 v[112:115], v[140:143], v[174:177], v[112:115]
	v_mfma_f32_16x16x32_bf16 v[96:99], v[84:87], v[182:185], v[96:99]
	v_mfma_f32_16x16x32_bf16 v[100:103], v[140:143], v[182:185], v[100:103]
	v_mfma_f32_16x16x32_bf16 v[80:83], v[84:87], v[190:193], v[80:83]
	v_mfma_f32_16x16x32_bf16 v[76:79], v[140:143], v[190:193], v[76:79]
	v_mfma_f32_16x16x32_bf16 v[124:127], v[136:139], v[170:173], v[124:127]
	v_mfma_f32_16x16x32_bf16 v[120:123], v[144:147], v[170:173], v[120:123]
	v_mfma_f32_16x16x32_bf16 v[116:119], v[136:139], v[178:181], v[116:119]
	v_mfma_f32_16x16x32_bf16 v[112:115], v[144:147], v[178:181], v[112:115]
	v_mfma_f32_16x16x32_bf16 v[96:99], v[136:139], v[186:189], v[96:99]
	v_mfma_f32_16x16x32_bf16 v[100:103], v[144:147], v[186:189], v[100:103]
	v_mfma_f32_16x16x32_bf16 v[80:83], v[136:139], v[194:197], v[80:83]
	v_mfma_f32_16x16x32_bf16 v[76:79], v[144:147], v[194:197], v[76:79]
	s_setprio 0
	s_barrier
	s_mov_b32 m0, s66
	v_lshl_add_u64 v[160:161], v[160:161], 0, s[8:9]
	ds_read_b128 v[198:201], v168
	ds_read_b128 v[210:213], v168 offset:1024
	ds_read_b128 v[214:217], v168 offset:2048
	ds_read_b128 v[218:221], v168 offset:3072
	global_load_lds_dwordx4 v[160:161], off
	v_lshl_add_u64 v[160:161], v[222:223], 0, s[8:9]
	s_mov_b32 m0, s67
	s_nop 0
	global_load_lds_dwordx4 v[160:161], off
	s_barrier
	s_waitcnt lgkmcnt(0)
	s_setprio 1
	s_waitcnt lgkmcnt(0)
	v_mfma_f32_16x16x32_bf16 v[128:131], v[198:201], v[156:159], v[128:131]
	v_mfma_f32_16x16x32_bf16 v[132:135], v[214:217], v[156:159], v[132:135]
	v_mfma_f32_16x16x32_bf16 v[104:107], v[198:201], v[174:177], v[104:107]
	v_mfma_f32_16x16x32_bf16 v[108:111], v[214:217], v[174:177], v[108:111]
	v_mfma_f32_16x16x32_bf16 v[88:91], v[198:201], v[182:185], v[88:91]
	v_mfma_f32_16x16x32_bf16 v[92:95], v[214:217], v[182:185], v[92:95]
	v_mfma_f32_16x16x32_bf16 v[68:71], v[198:201], v[190:193], v[68:71]
	v_mfma_f32_16x16x32_bf16 v[72:75], v[214:217], v[190:193], v[72:75]
	v_mfma_f32_16x16x32_bf16 v[128:131], v[210:213], v[170:173], v[128:131]
	v_mfma_f32_16x16x32_bf16 v[132:135], v[218:221], v[170:173], v[132:135]
	v_mfma_f32_16x16x32_bf16 v[104:107], v[210:213], v[178:181], v[104:107]
	v_mfma_f32_16x16x32_bf16 v[108:111], v[218:221], v[178:181], v[108:111]
	v_mfma_f32_16x16x32_bf16 v[88:91], v[210:213], v[186:189], v[88:91]
	v_mfma_f32_16x16x32_bf16 v[92:95], v[218:221], v[186:189], v[92:95]
	v_mfma_f32_16x16x32_bf16 v[68:71], v[210:213], v[194:197], v[68:71]
	v_mfma_f32_16x16x32_bf16 v[72:75], v[218:221], v[194:197], v[72:75]
	s_setprio 0
	s_mov_b32 m0, s23
	v_lshl_add_u64 v[160:161], v[224:225], 0, s[8:9]
	s_barrier
	ds_read_b128 v[156:159], v165 offset:49152
	ds_read_b128 v[170:173], v165 offset:50176
	ds_read_b128 v[174:177], v165 offset:51200
	ds_read_b128 v[178:181], v165 offset:52224
	ds_read_b128 v[182:185], v165 offset:53248
	ds_read_b128 v[186:189], v165 offset:54272
	ds_read_b128 v[190:193], v165 offset:55296
	ds_read_b128 v[194:197], v165 offset:56320
	global_load_lds_dwordx4 v[160:161], off
	v_lshl_add_u64 v[160:161], v[226:227], 0, s[8:9]
	s_mov_b32 m0, s24
	s_nop 0
	global_load_lds_dwordx4 v[160:161], off
	s_barrier
	s_waitcnt lgkmcnt(0)
	s_setprio 1
	s_waitcnt lgkmcnt(0)
	v_mfma_f32_16x16x32_bf16 v[60:63], v[84:87], v[156:159], v[60:63]
	v_mfma_f32_16x16x32_bf16 v[64:67], v[140:143], v[156:159], v[64:67]
	v_mfma_f32_16x16x32_bf16 v[44:47], v[84:87], v[174:177], v[44:47]
	v_mfma_f32_16x16x32_bf16 v[48:51], v[140:143], v[174:177], v[48:51]
	v_mfma_f32_16x16x32_bf16 v[28:31], v[84:87], v[182:185], v[28:31]
	v_mfma_f32_16x16x32_bf16 v[32:35], v[140:143], v[182:185], v[32:35]
	v_mfma_f32_16x16x32_bf16 v[12:15], v[84:87], v[190:193], v[12:15]
	v_mfma_f32_16x16x32_bf16 v[8:11], v[140:143], v[190:193], v[8:11]
	v_mfma_f32_16x16x32_bf16 v[60:63], v[136:139], v[170:173], v[60:63]
	v_mfma_f32_16x16x32_bf16 v[64:67], v[144:147], v[170:173], v[64:67]
	v_mfma_f32_16x16x32_bf16 v[44:47], v[136:139], v[178:181], v[44:47]
	v_mfma_f32_16x16x32_bf16 v[48:51], v[144:147], v[178:181], v[48:51]
	v_mfma_f32_16x16x32_bf16 v[28:31], v[136:139], v[186:189], v[28:31]
	v_mfma_f32_16x16x32_bf16 v[32:35], v[144:147], v[186:189], v[32:35]
	v_mfma_f32_16x16x32_bf16 v[12:15], v[136:139], v[194:197], v[12:15]
	v_mfma_f32_16x16x32_bf16 v[8:11], v[144:147], v[194:197], v[8:11]
	s_setprio 0
	s_barrier
	s_add_u32 s16, s16, 0x40080
	s_addc_u32 s17, s17, 0
	s_mov_b32 m0, s68
	v_lshl_add_u64 v[84:85], s[16:17], 0, v[150:151]
	global_load_lds_dwordx4 v[84:85], off
	v_lshl_add_u64 v[84:85], s[16:17], 0, v[154:155]
	s_mov_b32 m0, s69
	s_nop 0
	global_load_lds_dwordx4 v[84:85], off
	s_waitcnt vmcnt(6)
	s_barrier
	s_setprio 1
	v_mfma_f32_16x16x32_bf16 v[52:55], v[198:201], v[156:159], v[52:55]
	v_mfma_f32_16x16x32_bf16 v[56:59], v[214:217], v[156:159], v[56:59]
	v_mfma_f32_16x16x32_bf16 v[36:39], v[198:201], v[174:177], v[36:39]
	v_mfma_f32_16x16x32_bf16 v[40:43], v[214:217], v[174:177], v[40:43]
	v_mfma_f32_16x16x32_bf16 v[20:23], v[198:201], v[182:185], v[20:23]
	v_mfma_f32_16x16x32_bf16 v[24:27], v[214:217], v[182:185], v[24:27]
	v_mfma_f32_16x16x32_bf16 v[4:7], v[198:201], v[190:193], v[4:7]
	v_mfma_f32_16x16x32_bf16 v[0:3], v[214:217], v[190:193], v[0:3]
	v_mfma_f32_16x16x32_bf16 v[52:55], v[210:213], v[170:173], v[52:55]
	v_mfma_f32_16x16x32_bf16 v[56:59], v[218:221], v[170:173], v[56:59]
	v_mfma_f32_16x16x32_bf16 v[36:39], v[210:213], v[178:181], v[36:39]
	v_mfma_f32_16x16x32_bf16 v[40:43], v[218:221], v[178:181], v[40:43]
	v_mfma_f32_16x16x32_bf16 v[20:23], v[210:213], v[186:189], v[20:23]
	v_mfma_f32_16x16x32_bf16 v[24:27], v[218:221], v[186:189], v[24:27]
	v_mfma_f32_16x16x32_bf16 v[4:7], v[210:213], v[194:197], v[4:7]
	v_mfma_f32_16x16x32_bf16 v[0:3], v[218:221], v[194:197], v[0:3]
	s_setprio 0
	s_add_i32 s56, s56, 2
	s_add_u32 s4, s4, 0x100
	s_addc_u32 s5, s5, 0
	s_cmp_lt_u32 s56, 6
	s_barrier
	s_cbranch_scc1 .LBB0_818
	s_cmpk_gt_u32 s13, 0xff
	s_cbranch_scc1 .Lus5
	s_barrier

.LBB0_897:
	s_add_u32 s67, s56, 0x100
	s_addc_u32 s68, s57, 0
	s_ashr_i32 s17, s16, 31
	s_lshl_b64 s[36:37], s[16:17], 19
	s_add_u32 s38, s10, s36
	s_addc_u32 s39, s11, s37
	s_and_b64 s[36:37], s[4:5], exec
	s_cselect_b32 s17, s39, s7
	s_cselect_b32 s69, s38, s6
	s_ashr_i32 s15, s14, 31
	s_lshl_b64 s[36:37], s[14:15], 19
	s_add_u32 s36, s20, s36
	s_addc_u32 s37, s21, s37
	s_and_b64 s[58:59], s[4:5], exec
	s_cselect_b32 s15, s37, s57
	s_cselect_b32 s70, s36, s56
	v_lshl_add_u64 v[140:141], s[6:7], 0, v[132:133]
	v_lshl_add_u64 v[142:143], s[6:7], 0, v[134:135]
	s_mov_b32 s71, -2
	s_mov_b64 s[56:57], 0
	s_getpc_b64 s[98:99]
	v_lshlrev_b32_e32 v246, 7, v202
	v_mov_b32_e32 v247, 0
	v_lshl_add_u64 v[246:247], v[246:247], 0, s[98:99]
.LBB0_898:
	v_add_u32_e32 v158, s64, v144
	s_add_u32 s26, s6, s56
	ds_read_b128 v[146:149], v158
	ds_read_b128 v[150:153], v158 offset:1024
	ds_read_b128 v[154:157], v158 offset:2048
	ds_read_b128 v[158:161], v158 offset:3072
	s_addc_u32 s27, s7, s57
	s_add_u32 s26, s26, 0x100
	s_addc_u32 s27, s27, 0
	s_add_u32 s58, s67, s56
	s_addc_u32 s59, s68, s57
	s_cmpk_eq_i32 s56, 0x700
	s_cselect_b32 s61, s17, s27
	s_cselect_b32 s60, s69, s26
	s_cselect_b32 s59, s15, s59
	s_cselect_b32 s58, s70, s58
	v_lshl_add_u64 v[194:195], v[140:141], 0, s[56:57]
	s_add_i32 m0, s3, 0xc000
	ds_read_b128 v[162:165], v145
	ds_read_b128 v[166:169], v145 offset:1024
	ds_read_b128 v[170:173], v145 offset:2048
	ds_read_b128 v[174:177], v145 offset:3072
	ds_read_b128 v[178:181], v145 offset:4096
	ds_read_b128 v[182:185], v145 offset:5120
	ds_read_b128 v[186:189], v145 offset:6144
	ds_read_b128 v[190:193], v145 offset:7168
	global_load_lds_dwordx4 v[194:195], off
	v_lshl_add_u64 v[194:195], v[142:143], 0, s[56:57]
	s_add_i32 m0, s3, 0xe000
	s_nop 0
	global_load_lds_dwordx4 v[194:195], off
	s_cmp_eq_u32 s71, 10
	s_cbranch_scc0 .Lct_g3
	global_load_dword v248, v[246:247], off
.Lct_g3:
	s_waitcnt lgkmcnt(8)
	s_barrier
	s_waitcnt lgkmcnt(0)
	s_setprio 1
	s_waitcnt lgkmcnt(0)
	v_mfma_f32_16x16x32_bf16 v[124:127], v[146:149], v[162:165], v[124:127]
	v_mfma_f32_16x16x32_bf16 v[120:123], v[154:157], v[162:165], v[120:123]
	v_mfma_f32_16x16x32_bf16 v[108:111], v[146:149], v[170:173], v[108:111]
	v_mfma_f32_16x16x32_bf16 v[104:107], v[154:157], v[170:173], v[104:107]
	v_mfma_f32_16x16x32_bf16 v[92:95], v[146:149], v[178:181], v[92:95]
	v_mfma_f32_16x16x32_bf16 v[88:91], v[154:157], v[178:181], v[88:91]
	v_mfma_f32_16x16x32_bf16 v[76:79], v[146:149], v[186:189], v[76:79]
	v_mfma_f32_16x16x32_bf16 v[72:75], v[154:157], v[186:189], v[72:75]
	v_mfma_f32_16x16x32_bf16 v[124:127], v[150:153], v[166:169], v[124:127]
	v_mfma_f32_16x16x32_bf16 v[120:123], v[158:161], v[166:169], v[120:123]
	v_mfma_f32_16x16x32_bf16 v[108:111], v[150:153], v[174:177], v[108:111]
	v_mfma_f32_16x16x32_bf16 v[104:107], v[158:161], v[174:177], v[104:107]
	v_mfma_f32_16x16x32_bf16 v[92:95], v[150:153], v[182:185], v[92:95]
	v_mfma_f32_16x16x32_bf16 v[88:91], v[158:161], v[182:185], v[88:91]
	v_mfma_f32_16x16x32_bf16 v[76:79], v[150:153], v[190:193], v[76:79]
	v_mfma_f32_16x16x32_bf16 v[72:75], v[158:161], v[190:193], v[72:75]
	s_setprio 0
	s_barrier
	s_add_i32 s26, s64, s22
	v_add_u32_e32 v209, s65, v144
	v_lshl_add_u64 v[218:219], s[58:59], 0, v[128:129]
	s_mov_b32 m0, s26
	ds_read_b128 v[194:197], v209
	ds_read_b128 v[198:201], v209 offset:1024
	ds_read_b128 v[210:213], v209 offset:2048
	ds_read_b128 v[214:217], v209 offset:3072
	global_load_lds_dwordx4 v[218:219], off
	v_lshl_add_u64 v[220:221], s[58:59], 0, v[130:131]
	s_add_i32 m0, s26, 0x2000
	s_nop 0
	global_load_lds_dwordx4 v[220:221], off
	s_barrier
	s_waitcnt lgkmcnt(0)
	s_setprio 1
	s_waitcnt lgkmcnt(0)
	v_mfma_f32_16x16x32_bf16 v[116:119], v[194:197], v[162:165], v[116:119]
	v_mfma_f32_16x16x32_bf16 v[112:115], v[210:213], v[162:165], v[112:115]
	v_mfma_f32_16x16x32_bf16 v[100:103], v[194:197], v[170:173], v[100:103]
	v_mfma_f32_16x16x32_bf16 v[96:99], v[210:213], v[170:173], v[96:99]
	v_mfma_f32_16x16x32_bf16 v[84:87], v[194:197], v[178:181], v[84:87]
	v_mfma_f32_16x16x32_bf16 v[80:83], v[210:213], v[178:181], v[80:83]
	v_mfma_f32_16x16x32_bf16 v[68:71], v[194:197], v[186:189], v[68:71]
	v_mfma_f32_16x16x32_bf16 v[64:67], v[210:213], v[186:189], v[64:67]
	v_mfma_f32_16x16x32_bf16 v[116:119], v[198:201], v[166:169], v[116:119]
	v_mfma_f32_16x16x32_bf16 v[112:115], v[214:217], v[166:169], v[112:115]
	v_mfma_f32_16x16x32_bf16 v[100:103], v[198:201], v[174:177], v[100:103]
	v_mfma_f32_16x16x32_bf16 v[96:99], v[214:217], v[174:177], v[96:99]
	v_mfma_f32_16x16x32_bf16 v[84:87], v[198:201], v[182:185], v[84:87]
	v_mfma_f32_16x16x32_bf16 v[80:83], v[214:217], v[182:185], v[80:83]
	v_mfma_f32_16x16x32_bf16 v[68:71], v[198:201], v[190:193], v[68:71]
	v_mfma_f32_16x16x32_bf16 v[64:67], v[214:217], v[190:193], v[64:67]
	s_setprio 0
	s_mov_b32 m0, s3
	v_lshl_add_u64 v[222:223], s[60:61], 0, v[128:129]
	s_barrier
	ds_read_b128 v[162:165], v145 offset:16384
	ds_read_b128 v[166:169], v145 offset:17408
	ds_read_b128 v[170:173], v145 offset:18432
	ds_read_b128 v[174:177], v145 offset:19456
	ds_read_b128 v[178:181], v145 offset:20480
	ds_read_b128 v[182:185], v145 offset:21504
	ds_read_b128 v[186:189], v145 offset:22528
	ds_read_b128 v[190:193], v145 offset:23552
	global_load_lds_dwordx4 v[222:223], off
	v_lshl_add_u64 v[224:225], s[60:61], 0, v[130:131]
	s_mov_b32 m0, s23
	s_nop 0
	global_load_lds_dwordx4 v[224:225], off
	s_barrier
	s_waitcnt lgkmcnt(0)
	s_setprio 1
	s_waitcnt lgkmcnt(0)
	v_mfma_f32_16x16x32_bf16 v[60:63], v[146:149], v[162:165], v[60:63]
	v_mfma_f32_16x16x32_bf16 v[56:59], v[154:157], v[162:165], v[56:59]
	v_mfma_f32_16x16x32_bf16 v[44:47], v[146:149], v[170:173], v[44:47]
	v_mfma_f32_16x16x32_bf16 v[40:43], v[154:157], v[170:173], v[40:43]
	v_mfma_f32_16x16x32_bf16 v[28:31], v[146:149], v[178:181], v[28:31]
	v_mfma_f32_16x16x32_bf16 v[24:27], v[154:157], v[178:181], v[24:27]
	v_mfma_f32_16x16x32_bf16 v[12:15], v[146:149], v[186:189], v[12:15]
	v_mfma_f32_16x16x32_bf16 v[8:11], v[154:157], v[186:189], v[8:11]
	v_mfma_f32_16x16x32_bf16 v[60:63], v[150:153], v[166:169], v[60:63]
	v_mfma_f32_16x16x32_bf16 v[56:59], v[158:161], v[166:169], v[56:59]
	v_mfma_f32_16x16x32_bf16 v[44:47], v[150:153], v[174:177], v[44:47]
	v_mfma_f32_16x16x32_bf16 v[40:43], v[158:161], v[174:177], v[40:43]
	v_mfma_f32_16x16x32_bf16 v[28:31], v[150:153], v[182:185], v[28:31]
	v_mfma_f32_16x16x32_bf16 v[24:27], v[158:161], v[182:185], v[24:27]
	v_mfma_f32_16x16x32_bf16 v[12:15], v[150:153], v[190:193], v[12:15]
	v_mfma_f32_16x16x32_bf16 v[8:11], v[158:161], v[190:193], v[8:11]
	s_setprio 0
	s_barrier
	s_add_u32 s72, s58, 0x40000
	s_addc_u32 s73, s59, 0
	s_add_i32 s26, s65, s22
	v_lshl_add_u64 v[146:147], s[72:73], 0, v[128:129]
	s_mov_b32 m0, s26
	s_nop 0
	global_load_lds_dwordx4 v[146:147], off
	v_lshl_add_u64 v[146:147], s[72:73], 0, v[130:131]
	s_add_i32 m0, s26, 0x2000
	s_nop 0
	global_load_lds_dwordx4 v[146:147], off
	s_waitcnt vmcnt(6)
	s_barrier
	s_setprio 1
	v_mfma_f32_16x16x32_bf16 v[52:55], v[194:197], v[162:165], v[52:55]
	v_mfma_f32_16x16x32_bf16 v[48:51], v[210:213], v[162:165], v[48:51]
	v_mfma_f32_16x16x32_bf16 v[36:39], v[194:197], v[170:173], v[36:39]
	v_mfma_f32_16x16x32_bf16 v[32:35], v[210:213], v[170:173], v[32:35]
	v_mfma_f32_16x16x32_bf16 v[20:23], v[194:197], v[178:181], v[20:23]
	v_mfma_f32_16x16x32_bf16 v[16:19], v[210:213], v[178:181], v[16:19]
	v_mfma_f32_16x16x32_bf16 v[4:7], v[194:197], v[186:189], v[4:7]
	v_mfma_f32_16x16x32_bf16 v[0:3], v[210:213], v[186:189], v[0:3]
	v_mfma_f32_16x16x32_bf16 v[52:55], v[198:201], v[166:169], v[52:55]
	v_mfma_f32_16x16x32_bf16 v[48:51], v[214:217], v[166:169], v[48:51]
	v_mfma_f32_16x16x32_bf16 v[36:39], v[198:201], v[174:177], v[36:39]
	v_mfma_f32_16x16x32_bf16 v[32:35], v[214:217], v[174:177], v[32:35]
	v_mfma_f32_16x16x32_bf16 v[20:23], v[198:201], v[182:185], v[20:23]
	v_mfma_f32_16x16x32_bf16 v[16:19], v[214:217], v[182:185], v[16:19]
	v_mfma_f32_16x16x32_bf16 v[4:7], v[198:201], v[190:193], v[4:7]
	v_mfma_f32_16x16x32_bf16 v[0:3], v[214:217], v[190:193], v[0:3]
	s_setprio 0
	s_add_i32 s26, 0, 0x18000
	v_add_u32_e32 v158, s26, v144
	s_barrier
	ds_read_b128 v[146:149], v158
	ds_read_b128 v[150:153], v158 offset:1024
	ds_read_b128 v[154:157], v158 offset:2048
	ds_read_b128 v[158:161], v158 offset:3072
	s_add_u32 s60, s60, 0x40000
	s_addc_u32 s61, s61, 0
	s_mov_b32 m0, s24
	v_lshl_add_u64 v[194:195], s[60:61], 0, v[128:129]
	ds_read_b128 v[162:165], v145 offset:32768
	ds_read_b128 v[166:169], v145 offset:33792
	ds_read_b128 v[170:173], v145 offset:34816
	ds_read_b128 v[174:177], v145 offset:35840
	ds_read_b128 v[178:181], v145 offset:36864
	ds_read_b128 v[182:185], v145 offset:37888
	ds_read_b128 v[186:189], v145 offset:38912
	ds_read_b128 v[190:193], v145 offset:39936
	global_load_lds_dwordx4 v[194:195], off
	v_lshl_add_u64 v[194:195], s[60:61], 0, v[130:131]
	s_mov_b32 m0, s25
	s_nop 0
	global_load_lds_dwordx4 v[194:195], off
	s_waitcnt lgkmcnt(8)
	s_barrier
	s_waitcnt lgkmcnt(0)
	s_setprio 1
	s_waitcnt lgkmcnt(0)
	v_mfma_f32_16x16x32_bf16 v[124:127], v[146:149], v[162:165], v[124:127]
	v_mfma_f32_16x16x32_bf16 v[120:123], v[154:157], v[162:165], v[120:123]
	v_mfma_f32_16x16x32_bf16 v[108:111], v[146:149], v[170:173], v[108:111]
	v_mfma_f32_16x16x32_bf16 v[104:107], v[154:157], v[170:173], v[104:107]
	v_mfma_f32_16x16x32_bf16 v[92:95], v[146:149], v[178:181], v[92:95]
	v_mfma_f32_16x16x32_bf16 v[88:91], v[154:157], v[178:181], v[88:91]
	v_mfma_f32_16x16x32_bf16 v[76:79], v[146:149], v[186:189], v[76:79]
	v_mfma_f32_16x16x32_bf16 v[72:75], v[154:157], v[186:189], v[72:75]
	v_mfma_f32_16x16x32_bf16 v[124:127], v[150:153], v[166:169], v[124:127]
	v_mfma_f32_16x16x32_bf16 v[120:123], v[158:161], v[166:169], v[120:123]
	v_mfma_f32_16x16x32_bf16 v[108:111], v[150:153], v[174:177], v[108:111]
	v_mfma_f32_16x16x32_bf16 v[104:107], v[158:161], v[174:177], v[104:107]
	v_mfma_f32_16x16x32_bf16 v[92:95], v[150:153], v[182:185], v[92:95]
	v_mfma_f32_16x16x32_bf16 v[88:91], v[158:161], v[182:185], v[88:91]
	v_mfma_f32_16x16x32_bf16 v[76:79], v[150:153], v[190:193], v[76:79]
	v_mfma_f32_16x16x32_bf16 v[72:75], v[158:161], v[190:193], v[72:75]
	s_setprio 0
	s_barrier
	s_add_i32 s27, 0, 0x1c000
	s_add_i32 s26, s26, s22
	v_add_u32_e32 v209, s27, v144
	v_lshl_add_u64 v[218:219], v[218:219], 0, s[8:9]
	s_mov_b32 m0, s26
	ds_read_b128 v[194:197], v209
	ds_read_b128 v[198:201], v209 offset:1024
	ds_read_b128 v[210:213], v209 offset:2048
	ds_read_b128 v[214:217], v209 offset:3072
	global_load_lds_dwordx4 v[218:219], off
	v_lshl_add_u64 v[218:219], v[220:221], 0, s[8:9]
	s_add_i32 m0, s26, 0x2000
	s_nop 0
	global_load_lds_dwordx4 v[218:219], off
	s_barrier
	s_waitcnt lgkmcnt(0)
	s_setprio 1
	s_waitcnt lgkmcnt(0)
	v_mfma_f32_16x16x32_bf16 v[116:119], v[194:197], v[162:165], v[116:119]
	v_mfma_f32_16x16x32_bf16 v[112:115], v[210:213], v[162:165], v[112:115]
	v_mfma_f32_16x16x32_bf16 v[100:103], v[194:197], v[170:173], v[100:103]
	v_mfma_f32_16x16x32_bf16 v[96:99], v[210:213], v[170:173], v[96:99]
	v_mfma_f32_16x16x32_bf16 v[84:87], v[194:197], v[178:181], v[84:87]
	v_mfma_f32_16x16x32_bf16 v[80:83], v[210:213], v[178:181], v[80:83]
	v_mfma_f32_16x16x32_bf16 v[68:71], v[194:197], v[186:189], v[68:71]
	v_mfma_f32_16x16x32_bf16 v[64:67], v[210:213], v[186:189], v[64:67]
	v_mfma_f32_16x16x32_bf16 v[116:119], v[198:201], v[166:169], v[116:119]
	v_mfma_f32_16x16x32_bf16 v[112:115], v[214:217], v[166:169], v[112:115]
	v_mfma_f32_16x16x32_bf16 v[100:103], v[198:201], v[174:177], v[100:103]
	v_mfma_f32_16x16x32_bf16 v[96:99], v[214:217], v[174:177], v[96:99]
	v_mfma_f32_16x16x32_bf16 v[84:87], v[198:201], v[182:185], v[84:87]
	v_mfma_f32_16x16x32_bf16 v[80:83], v[214:217], v[182:185], v[80:83]
	v_mfma_f32_16x16x32_bf16 v[68:71], v[198:201], v[190:193], v[68:71]
	v_mfma_f32_16x16x32_bf16 v[64:67], v[214:217], v[190:193], v[64:67]
	s_setprio 0
	s_mov_b32 m0, s33
	v_lshl_add_u64 v[218:219], v[222:223], 0, s[8:9]
	s_barrier
	ds_read_b128 v[162:165], v145 offset:49152
	ds_read_b128 v[166:169], v145 offset:50176
	ds_read_b128 v[170:173], v145 offset:51200
	ds_read_b128 v[174:177], v145 offset:52224
	ds_read_b128 v[178:181], v145 offset:53248
	ds_read_b128 v[182:185], v145 offset:54272
	ds_read_b128 v[186:189], v145 offset:55296
	ds_read_b128 v[190:193], v145 offset:56320
	global_load_lds_dwordx4 v[218:219], off
	v_lshl_add_u64 v[218:219], v[224:225], 0, s[8:9]
	s_mov_b32 m0, s62
	s_nop 0
	global_load_lds_dwordx4 v[218:219], off
	s_barrier
	s_waitcnt lgkmcnt(0)
	s_setprio 1
	s_waitcnt lgkmcnt(0)
	v_mfma_f32_16x16x32_bf16 v[60:63], v[146:149], v[162:165], v[60:63]
	v_mfma_f32_16x16x32_bf16 v[56:59], v[154:157], v[162:165], v[56:59]
	v_mfma_f32_16x16x32_bf16 v[44:47], v[146:149], v[170:173], v[44:47]
	v_mfma_f32_16x16x32_bf16 v[40:43], v[154:157], v[170:173], v[40:43]
	v_mfma_f32_16x16x32_bf16 v[28:31], v[146:149], v[178:181], v[28:31]
	v_mfma_f32_16x16x32_bf16 v[24:27], v[154:157], v[178:181], v[24:27]
	v_mfma_f32_16x16x32_bf16 v[12:15], v[146:149], v[186:189], v[12:15]
	v_mfma_f32_16x16x32_bf16 v[8:11], v[154:157], v[186:189], v[8:11]
	v_mfma_f32_16x16x32_bf16 v[60:63], v[150:153], v[166:169], v[60:63]
	v_mfma_f32_16x16x32_bf16 v[56:59], v[158:161], v[166:169], v[56:59]
	v_mfma_f32_16x16x32_bf16 v[44:47], v[150:153], v[174:177], v[44:47]
	v_mfma_f32_16x16x32_bf16 v[40:43], v[158:161], v[174:177], v[40:43]
	v_mfma_f32_16x16x32_bf16 v[28:31], v[150:153], v[182:185], v[28:31]
	v_mfma_f32_16x16x32_bf16 v[24:27], v[158:161], v[182:185], v[24:27]
	v_mfma_f32_16x16x32_bf16 v[12:15], v[150:153], v[190:193], v[12:15]
	v_mfma_f32_16x16x32_bf16 v[8:11], v[158:161], v[190:193], v[8:11]
	s_setprio 0
	s_barrier
	s_add_u32 s58, s58, 0x40080
	s_addc_u32 s59, s59, 0
	s_add_i32 s26, s27, s22
	v_lshl_add_u64 v[146:147], s[58:59], 0, v[128:129]
	s_mov_b32 m0, s26
	s_nop 0
	global_load_lds_dwordx4 v[146:147], off
	v_lshl_add_u64 v[146:147], s[58:59], 0, v[130:131]
	s_add_i32 m0, s26, 0x2000
	s_nop 0
	global_load_lds_dwordx4 v[146:147], off
	s_waitcnt vmcnt(6)
	s_barrier
	s_setprio 1
	v_mfma_f32_16x16x32_bf16 v[52:55], v[194:197], v[162:165], v[52:55]
	v_mfma_f32_16x16x32_bf16 v[48:51], v[210:213], v[162:165], v[48:51]
	v_mfma_f32_16x16x32_bf16 v[36:39], v[194:197], v[170:173], v[36:39]
	v_mfma_f32_16x16x32_bf16 v[32:35], v[210:213], v[170:173], v[32:35]
	v_mfma_f32_16x16x32_bf16 v[20:23], v[194:197], v[178:181], v[20:23]
	v_mfma_f32_16x16x32_bf16 v[16:19], v[210:213], v[178:181], v[16:19]
	v_mfma_f32_16x16x32_bf16 v[4:7], v[194:197], v[186:189], v[4:7]
	v_mfma_f32_16x16x32_bf16 v[0:3], v[210:213], v[186:189], v[0:3]
	v_mfma_f32_16x16x32_bf16 v[52:55], v[198:201], v[166:169], v[52:55]
	v_mfma_f32_16x16x32_bf16 v[48:51], v[214:217], v[166:169], v[48:51]
	v_mfma_f32_16x16x32_bf16 v[36:39], v[198:201], v[174:177], v[36:39]
	v_mfma_f32_16x16x32_bf16 v[32:35], v[214:217], v[174:177], v[32:35]
	v_mfma_f32_16x16x32_bf16 v[20:23], v[198:201], v[182:185], v[20:23]
	v_mfma_f32_16x16x32_bf16 v[16:19], v[214:217], v[182:185], v[16:19]
	v_mfma_f32_16x16x32_bf16 v[4:7], v[198:201], v[190:193], v[4:7]
	v_mfma_f32_16x16x32_bf16 v[0:3], v[214:217], v[190:193], v[0:3]
	s_setprio 0
	s_add_i32 s71, s71, 2
	s_add_u32 s56, s56, 0x100
	s_addc_u32 s57, s57, 0
	s_cmp_gt_u32 s71, 13
	s_barrier
	s_cbranch_scc0 .LBB0_898
	s_add_u32 s56, s67, 0xffffff00
	s_addc_u32 s57, s68, -1
	s_andn2_b64 vcc, exec, s[4:5]
	s_cbranch_vccnz .LBB0_889
	v_mov_b32_e32 v0, 0
	s_mov_b32 s13, s14
	s_mov_b32 s2, s16
	s_mov_b64 s[6:7], s[38:39]
	s_mov_b32 s63, s66
	v_mov_b32_e32 v1, v0
	v_mov_b32_e32 v2, v0
	v_mov_b32_e32 v3, v0
	v_mov_b32_e32 v4, v0
	v_mov_b32_e32 v5, v0
	v_mov_b32_e32 v6, v0
	v_mov_b32_e32 v7, v0
	v_mov_b32_e32 v16, v0
	v_mov_b32_e32 v17, v0
	v_mov_b32_e32 v18, v0
	v_mov_b32_e32 v19, v0
	v_mov_b32_e32 v20, v0
	v_mov_b32_e32 v21, v0
	v_mov_b32_e32 v22, v0
	v_mov_b32_e32 v23, v0
	v_mov_b32_e32 v32, v0
	v_mov_b32_e32 v33, v0
	v_mov_b32_e32 v34, v0
	v_mov_b32_e32 v35, v0
	v_mov_b32_e32 v36, v0
	v_mov_b32_e32 v37, v0
	v_mov_b32_e32 v38, v0
	v_mov_b32_e32 v39, v0
	v_mov_b32_e32 v48, v0
	v_mov_b32_e32 v49, v0
	v_mov_b32_e32 v50, v0
	v_mov_b32_e32 v51, v0
	v_mov_b32_e32 v52, v0
	v_mov_b32_e32 v53, v0
	v_mov_b32_e32 v54, v0
	v_mov_b32_e32 v55, v0
	v_mov_b32_e32 v8, v0
	v_mov_b32_e32 v9, v0
	v_mov_b32_e32 v10, v0
	v_mov_b32_e32 v11, v0
	v_mov_b32_e32 v12, v0
	v_mov_b32_e32 v13, v0
	v_mov_b32_e32 v14, v0
	v_mov_b32_e32 v15, v0
	v_mov_b32_e32 v24, v0
	v_mov_b32_e32 v25, v0
	v_mov_b32_e32 v26, v0
	v_mov_b32_e32 v27, v0
	v_mov_b32_e32 v28, v0
	v_mov_b32_e32 v29, v0
	v_mov_b32_e32 v30, v0
	v_mov_b32_e32 v31, v0
	v_mov_b32_e32 v40, v0
	v_mov_b32_e32 v41, v0
	v_mov_b32_e32 v42, v0
	v_mov_b32_e32 v43, v0
	v_mov_b32_e32 v44, v0
	v_mov_b32_e32 v45, v0
	v_mov_b32_e32 v46, v0
	v_mov_b32_e32 v47, v0
	v_mov_b32_e32 v56, v0
	v_mov_b32_e32 v57, v0
	v_mov_b32_e32 v58, v0
	v_mov_b32_e32 v59, v0
	v_mov_b32_e32 v60, v0
	v_mov_b32_e32 v61, v0
	v_mov_b32_e32 v62, v0
	v_mov_b32_e32 v63, v0
	v_mov_b32_e32 v64, v0
	v_mov_b32_e32 v65, v0
	v_mov_b32_e32 v66, v0
	v_mov_b32_e32 v67, v0
	v_mov_b32_e32 v68, v0
	v_mov_b32_e32 v69, v0
	v_mov_b32_e32 v70, v0
	v_mov_b32_e32 v71, v0
	v_mov_b32_e32 v80, v0
	v_mov_b32_e32 v81, v0
	v_mov_b32_e32 v82, v0
	v_mov_b32_e32 v83, v0
	v_mov_b32_e32 v84, v0
	v_mov_b32_e32 v85, v0
	v_mov_b32_e32 v86, v0
	v_mov_b32_e32 v87, v0
	v_mov_b32_e32 v96, v0
	v_mov_b32_e32 v97, v0
	v_mov_b32_e32 v98, v0
	v_mov_b32_e32 v99, v0
	v_mov_b32_e32 v100, v0
	v_mov_b32_e32 v101, v0
	v_mov_b32_e32 v102, v0
	v_mov_b32_e32 v103, v0
	v_mov_b32_e32 v112, v0
	v_mov_b32_e32 v113, v0
	v_mov_b32_e32 v114, v0
	v_mov_b32_e32 v115, v0
	v_mov_b32_e32 v116, v0
	v_mov_b32_e32 v117, v0
	v_mov_b32_e32 v118, v0
	v_mov_b32_e32 v119, v0
	v_mov_b32_e32 v72, v0
	v_mov_b32_e32 v73, v0
	v_mov_b32_e32 v74, v0
	v_mov_b32_e32 v75, v0
	v_mov_b32_e32 v76, v0
	v_mov_b32_e32 v77, v0
	v_mov_b32_e32 v78, v0
	v_mov_b32_e32 v79, v0
	v_mov_b32_e32 v88, v0
	v_mov_b32_e32 v89, v0
	v_mov_b32_e32 v90, v0
	v_mov_b32_e32 v91, v0
	v_mov_b32_e32 v92, v0
	v_mov_b32_e32 v93, v0
	v_mov_b32_e32 v94, v0
	v_mov_b32_e32 v95, v0
	v_mov_b32_e32 v104, v0
	v_mov_b32_e32 v105, v0
	v_mov_b32_e32 v106, v0
	v_mov_b32_e32 v107, v0
	v_mov_b32_e32 v108, v0
	v_mov_b32_e32 v109, v0
	v_mov_b32_e32 v110, v0
	v_mov_b32_e32 v111, v0
	v_mov_b32_e32 v120, v0
	v_mov_b32_e32 v121, v0
	v_mov_b32_e32 v122, v0
	v_mov_b32_e32 v123, v0
	v_mov_b32_e32 v124, v0
	v_mov_b32_e32 v125, v0
	v_mov_b32_e32 v126, v0
	v_mov_b32_e32 v127, v0
	s_andn2_b64 vcc, exec, s[0:1]
	s_cbranch_vccnz .LBB0_890
